# LRU conv tile with a 272-byte row pitch in otherwise unused LDS: MFMA A-fragment reads and gate-stage reads free of bank conflicts
# baseline (speedup 1.0000x reference)
.LBB0_926:
	s_mul_i32 vcc_lo, s70, 0x1100
	s_cmp_lt_u32 s70, 5
	s_mov_b32 vcc_hi, 0x1a000
	s_cselect_b32 vcc_hi, vcc_hi, 0x1af00
	s_add_i32 vcc_lo, vcc_lo, vcc_hi
	v_lshlrev_b32_e32 v240, 2, v106
	v_add_u32_e32 v240, vcc_lo, v240
	v_and_b32_e32 v241, 15, v106
	v_lshrrev_b32_e32 v242, 4, v106
	v_mul_u32_u24_e32 v243, 0x110, v241
	v_lshlrev_b32_e32 v241, 2, v241
	v_mul_u32_u24_e32 v244, 0x440, v242
	v_lshlrev_b32_e32 v242, 5, v242
	v_add3_u32 v241, v241, v244, vcc_lo
	v_add3_u32 v242, v242, v243, vcc_lo
	s_add_i32 s20, s25, 0x7f
	s_lshr_b32 s30, s20, 7
	s_and_b64 s[20:21], s[68:69], exec
	s_cselect_b32 s38, s76, 0x2984000
	s_ashr_i32 s29, s28, 31
	s_lshl_b64 s[26:27], s[26:27], 7
	s_lshl_b64 s[20:21], s[28:29], 12
	s_waitcnt vmcnt(12)
	v_mov_b32_e32 v67, v66
	v_mov_b32_e32 v68, v66
	v_mov_b32_e32 v69, v66
	s_waitcnt vmcnt(10)
	v_mov_b32_e32 v71, v70
	v_mov_b32_e32 v72, v70
	v_mov_b32_e32 v73, v70
	s_waitcnt vmcnt(8)
	v_mov_b32_e32 v75, v74
	v_mov_b32_e32 v76, v74
	v_mov_b32_e32 v77, v74
	s_waitcnt vmcnt(5)
	v_mov_b32_e32 v79, v78
	v_mov_b32_e32 v80, v78
	v_mov_b32_e32 v81, v78
	v_mov_b32_e32 v83, v82
	v_mov_b32_e32 v84, v82
	v_mov_b32_e32 v85, v82
	v_mov_b32_e32 v87, v86
	v_mov_b32_e32 v88, v86
	v_mov_b32_e32 v89, v86
	v_mov_b32_e32 v95, v94
	v_mov_b32_e32 v96, v94
	v_mov_b32_e32 v97, v94
	v_mov_b32_e32 v91, v90
	v_mov_b32_e32 v92, v90
	v_mov_b32_e32 v93, v90
	s_add_i32 s31, s25, -16
	v_lshl_add_u64 v[158:159], v[116:117], 0, s[26:27]
	s_lshl_b32 s38, s38, 2
	s_mov_b32 s39, s49
	s_mov_b32 s80, 0
.LBB0_927:
	s_cmp_lt_u32 s39, s25
	s_cselect_b64 s[28:29], -1, 0
	s_add_i32 s80, s80, 1
	s_cmp_lt_u32 s80, s30
	s_cselect_b64 s[26:27], -1, 0
	s_cmp_ge_u32 s39, s25
	s_cbranch_scc1 .LBB0_933
	s_waitcnt vmcnt(32)
	v_fma_f32 v98, v173, v144, v172
	v_fma_f32 v99, v173, v161, v172
	v_fmac_f32_e32 v98, v174, v161
	v_fmac_f32_e32 v99, v174, v160
	v_fmac_f32_e32 v98, v175, v160
	v_fmac_f32_e32 v99, v175, v129
	v_fmac_f32_e32 v98, v176, v129
	v_fmac_f32_e32 v99, v176, v128
	ds_write_b32 v240, v98 offset:0
	ds_write_b32 v240, v99 offset:272
	v_fma_f32 v98, v173, v160, v172
	v_fma_f32 v99, v173, v129, v172
	v_fmac_f32_e32 v98, v174, v129
	v_fmac_f32_e32 v99, v174, v128
	v_fmac_f32_e32 v98, v175, v128
	v_fmac_f32_e32 v99, v175, v133
	v_fmac_f32_e32 v98, v176, v133
	v_fmac_f32_e32 v99, v176, v132
	ds_write_b32 v240, v98 offset:544
	ds_write_b32 v240, v99 offset:816
	v_fma_f32 v98, v173, v128, v172
	v_fma_f32 v99, v173, v133, v172
	v_fmac_f32_e32 v98, v174, v133
	v_fmac_f32_e32 v99, v174, v132
	v_fmac_f32_e32 v98, v175, v132
	v_fmac_f32_e32 v99, v175, v137
	v_fmac_f32_e32 v98, v176, v137
	v_fmac_f32_e32 v99, v176, v136
	ds_write_b32 v240, v98 offset:1088
	ds_write_b32 v240, v99 offset:1360
	v_fma_f32 v98, v173, v132, v172
	v_fma_f32 v99, v173, v137, v172
	v_fmac_f32_e32 v98, v174, v137
	v_fmac_f32_e32 v99, v174, v136
	v_fmac_f32_e32 v98, v175, v136
	v_fmac_f32_e32 v99, v175, v141
	v_fmac_f32_e32 v98, v176, v141
	v_fmac_f32_e32 v99, v176, v140
	ds_write_b32 v240, v98 offset:1632
	ds_write_b32 v240, v99 offset:1904
	v_fma_f32 v98, v173, v136, v172
	v_fma_f32 v99, v173, v141, v172
	v_fmac_f32_e32 v98, v174, v141
	v_fmac_f32_e32 v99, v174, v140
	v_fmac_f32_e32 v98, v175, v140
	v_fmac_f32_e32 v99, v175, v147
	v_fmac_f32_e32 v98, v176, v147
	v_fmac_f32_e32 v99, v176, v146
	ds_write_b32 v240, v98 offset:2176
	ds_write_b32 v240, v99 offset:2448
	v_fma_f32 v98, v173, v140, v172
	v_fma_f32 v99, v173, v147, v172
	v_fmac_f32_e32 v98, v174, v147
	v_fmac_f32_e32 v99, v174, v146
	v_fmac_f32_e32 v98, v175, v146
	v_fmac_f32_e32 v99, v175, v151
	v_fmac_f32_e32 v98, v176, v151
	v_fmac_f32_e32 v99, v176, v150
	ds_write_b32 v240, v98 offset:2720
	ds_write_b32 v240, v99 offset:2992
	v_fma_f32 v98, v173, v146, v172
	v_fma_f32 v99, v173, v151, v172
	v_fmac_f32_e32 v98, v174, v151
	v_fmac_f32_e32 v99, v174, v150
	v_fmac_f32_e32 v98, v175, v150
	v_fmac_f32_e32 v99, v175, v154
	v_fmac_f32_e32 v98, v176, v154
	v_fmac_f32_e32 v99, v176, v155
	ds_write_b32 v240, v98 offset:3264
	ds_write_b32 v240, v99 offset:3536
	v_fma_f32 v98, v173, v150, v172
	v_fma_f32 v99, v173, v154, v172
	v_fmac_f32_e32 v98, v174, v154
	v_fmac_f32_e32 v99, v174, v155
	v_fmac_f32_e32 v98, v175, v155
	v_fmac_f32_e32 v99, v175, v157
	v_mov_b32_e32 v144, v155
	v_fmac_f32_e32 v98, v176, v157
	v_fmac_f32_e32 v99, v176, v156
	s_cmp_lg_u32 s31, s39
	ds_write_b32 v240, v98 offset:3808
	ds_write_b32 v240, v99 offset:4080
	s_cbranch_scc1 .LBB0_930
	s_load_dwordx2 s[54:55], s[40:41], 0xb8
	s_waitcnt lgkmcnt(0)
	s_add_u32 s54, s54, s38
	s_addc_u32 s55, s55, 0
	s_add_u32 s54, s54, s20
	s_addc_u32 s55, s55, s21
	v_lshl_add_u64 v[98:99], v[118:119], 2, s[54:55]
	v_add_co_u32_e32 v100, vcc, 0x1000, v98
	global_store_dword v[98:99], v155, off
	s_nop 0
	v_addc_co_u32_e32 v101, vcc, 0, v99, vcc
	v_add_co_u32_e32 v98, vcc, 0x2000, v98
	global_store_dword v[100:101], v157, off
	s_nop 0
	v_addc_co_u32_e32 v99, vcc, 0, v99, vcc
	global_store_dword v[98:99], v156, off

.LBB0_932:
	s_waitcnt lgkmcnt(0)
	ds_read_b128 v[98:101], v242
	ds_read_b128 v[102:105], v242 offset:16
	ds_read_b128 v[166:169], v242 offset:128
	ds_read_b128 v[178:181], v242 offset:144
	ds_read2_b32 v[182:183], v241 offset1:16
	ds_read2_b32 v[226:227], v241 offset0:68 offset1:84
	ds_read2_b32 v[228:229], v241 offset0:136 offset1:152
	ds_read2_b32 v[230:231], v241 offset0:204 offset1:220
	ds_read2_b32 v[232:233], v241 offset0:32 offset1:48
	ds_read2_b32 v[234:235], v241 offset0:100 offset1:116
	ds_read2_b32 v[236:237], v241 offset0:168 offset1:184
	ds_read2_b32 v[238:239], v241 offset0:236 offset1:252
	s_waitcnt lgkmcnt(11)
	v_cvt_pk_bf16_f32 v162, v98, v99
	v_cvt_pk_bf16_f32 v163, v100, v101
	s_waitcnt lgkmcnt(10)
	v_cvt_pk_bf16_f32 v164, v102, v103
	v_cvt_pk_bf16_f32 v165, v104, v105
	s_waitcnt lgkmcnt(9)
	v_cvt_pk_bf16_f32 v166, v166, v167
	v_cvt_pk_bf16_f32 v167, v168, v169
	s_waitcnt lgkmcnt(8)
	v_cvt_pk_bf16_f32 v168, v178, v179
	v_cvt_pk_bf16_f32 v169, v180, v181
	v_mfma_f32_16x16x32_bf16 v[98:101], v[162:165], v[6:9], v[66:69]
	s_nop 0
	v_mfma_f32_16x16x32_bf16 v[178:181], v[166:169], v[2:5], v[98:101]
	v_mfma_f32_16x16x32_bf16 v[190:193], v[162:165], v[34:37], v[82:85]
	v_mfma_f32_16x16x32_bf16 v[190:193], v[166:169], v[38:41], v[190:193]
	s_nop 5
	v_mul_f32_e32 v98, 0xbfb8aa3b, v178
	v_exp_f32_e32 v98, v98
	v_mfma_f32_16x16x32_bf16 v[102:105], v[162:165], v[10:13], v[70:73]
	v_add_f32_e32 v98, 1.0, v98
	v_rcp_f32_e32 v98, v98
	v_mul_f32_e32 v99, 0xbfb8aa3b, v190
	v_exp_f32_e32 v99, v99
	v_mfma_f32_16x16x32_bf16 v[194:197], v[166:169], v[14:17], v[102:105]
	v_mul_f32_e32 v98, v121, v98
	v_exp_f32_e32 v145, v98
	v_add_f32_e32 v98, 1.0, v99
	v_mul_f32_e32 v102, 0xbfb8aa3b, v179
	v_rcp_f32_e32 v103, v98
	v_fma_f32 v104, -v145, v145, 1.0 clamp
	s_nop 0
	v_exp_f32_e32 v178, v102
	v_sqrt_f32_e32 v104, v104
	s_waitcnt lgkmcnt(0)
	v_mul_f32_e32 v102, v103, v182
	v_mul_f32_e32 v182, 0xbfb8aa3b, v191
	v_add_f32_e32 v178, 1.0, v178
	v_mul_f32_e32 v179, v104, v102
	v_mfma_f32_16x16x32_bf16 v[102:105], v[162:165], v[42:45], v[86:89]
	v_rcp_f32_e32 v178, v178
	v_exp_f32_e32 v182, v182
	v_mul_f32_e32 v190, 0xbfb8aa3b, v195
	v_mfma_f32_16x16x32_bf16 v[198:201], v[166:169], v[46:49], v[102:105]
	v_exp_f32_e32 v190, v190
	v_add_f32_e32 v182, 1.0, v182
	v_rcp_f32_e32 v182, v182
	s_nop 0
	v_mul_f32_e32 v102, v121, v178
	v_exp_f32_e32 v178, v102
	v_mfma_f32_16x16x32_bf16 v[102:105], v[162:165], v[50:53], v[94:97]
	v_fma_f32 v185, -v178, v178, 1.0 clamp
	v_mfma_f32_16x16x32_bf16 v[202:205], v[166:169], v[54:57], v[102:105]
	s_nop 0
	s_nop 4
	v_mul_f32_e32 v102, 0xbfb8aa3b, v180
	v_mfma_f32_16x16x32_bf16 v[186:189], v[162:165], v[18:21], v[74:77]
	v_exp_f32_e32 v180, v102
	v_mfma_f32_16x16x32_bf16 v[98:101], v[162:165], v[26:29], v[78:81]
	v_mfma_f32_16x16x32_bf16 v[102:105], v[162:165], v[58:61], v[90:93]
	v_sqrt_f32_e32 v164, v185
	v_add_f32_e32 v165, 1.0, v180
	v_mfma_f32_16x16x32_bf16 v[186:189], v[166:169], v[22:25], v[186:189]
	v_rcp_f32_e32 v165, v165
	s_nop 0
	v_mul_f32_e32 v162, v182, v226
	v_mul_f32_e32 v162, v164, v162
	v_mfma_f32_16x16x32_bf16 v[98:101], v[166:169], v[30:33], v[98:101]
	v_mul_f32_e32 v165, v121, v165
	v_mul_f32_e32 v182, 0xbfb8aa3b, v194
	v_exp_f32_e32 v182, v182
	v_mfma_f32_16x16x32_bf16 v[102:105], v[166:169], v[62:65], v[102:105]
	v_mul_f32_e32 v166, 0xbfb8aa3b, v192
	v_exp_f32_e32 v166, v166
	v_exp_f32_e32 v168, v165
	s_nop 0
	v_mul_f32_e32 v98, 0xbfb8aa3b, v98
	v_exp_f32_e32 v98, v98
	v_add_f32_e32 v164, 1.0, v166
	v_rcp_f32_e32 v166, v164
	v_mul_f32_e32 v164, 0xbfb8aa3b, v181
	v_exp_f32_e32 v169, v164
	v_fma_f32 v167, -v168, v168, 1.0 clamp
	s_nop 0
	v_sqrt_f32_e32 v167, v167
	v_add_f32_e32 v169, 1.0, v169
	v_mul_f32_e32 v164, v166, v228
	v_mul_f32_e32 v166, 0xbfb8aa3b, v193
	v_exp_f32_e32 v166, v166
	v_rcp_f32_e32 v169, v169
	v_mul_f32_e32 v164, v167, v164
	v_add_f32_e32 v98, 1.0, v98
	v_add_f32_e32 v166, 1.0, v166
	v_rcp_f32_e32 v180, v166
	v_mul_f32_e32 v169, v121, v169
	v_exp_f32_e32 v169, v169
	v_rcp_f32_e32 v98, v98
	v_mul_f32_e32 v102, 0xbfb8aa3b, v102
	v_mul_f32_e32 v166, v180, v230
	v_add_f32_e32 v180, 1.0, v182
	v_fma_f32 v181, -v169, v169, 1.0 clamp
	v_rcp_f32_e32 v180, v180
	v_mul_f32_e32 v182, 0xbfb8aa3b, v198
	v_sqrt_f32_e32 v181, v181
	v_exp_f32_e32 v182, v182
	v_mul_f32_e32 v180, v120, v180
	v_exp_f32_e32 v180, v180
	v_mul_f32_e32 v166, v181, v166
	v_add_f32_e32 v181, 1.0, v182
	v_rcp_f32_e32 v181, v181
	v_fma_f32 v185, -v180, v180, 1.0 clamp
	v_add_u32_e32 v182, 0x1000, v109
	v_sqrt_f32_e32 v185, v185
	ds_write2_b32 v182, v145, v180 offset1:16
	v_mul_f32_e32 v145, v181, v183
	v_mul_f32_e32 v183, 0xbfb8aa3b, v199
	v_exp_f32_e32 v183, v183
	v_add_f32_e32 v180, 1.0, v190
	v_mul_f32_e32 v145, v185, v145
	v_rcp_f32_e32 v180, v180
	v_add_u32_e32 v181, 0x2000, v109
	ds_write2_b32 v181, v179, v145 offset1:16
	v_add_f32_e32 v145, 1.0, v183
	v_mul_f32_e32 v179, 0xbfb8aa3b, v196
	v_rcp_f32_e32 v145, v145
	v_exp_f32_e32 v179, v179
	v_mul_f32_e32 v180, v120, v180
	v_exp_f32_e32 v180, v180
	v_mul_f32_e32 v145, v145, v227
	v_add_f32_e32 v163, 1.0, v179
	v_rcp_f32_e32 v163, v163
	ds_write2_b32 v182, v178, v180 offset0:64 offset1:80
	v_fma_f32 v178, -v180, v180, 1.0 clamp
	v_sqrt_f32_e32 v178, v178
	v_mul_f32_e32 v163, v120, v163
	v_exp_f32_e32 v163, v163
	v_mul_f32_e32 v98, v122, v98
	v_mul_f32_e32 v145, v178, v145
	v_mul_f32_e32 v178, 0xbfb8aa3b, v200
	v_exp_f32_e32 v178, v178
	ds_write2_b32 v181, v162, v145 offset0:64 offset1:80
	ds_write2_b32 v182, v168, v163 offset0:128 offset1:144
	v_fma_f32 v162, -v163, v163, 1.0 clamp
	v_mul_f32_e32 v163, 0xbfb8aa3b, v197
	v_exp_f32_e32 v163, v163
	v_add_f32_e32 v145, 1.0, v178
	v_rcp_f32_e32 v145, v145
	v_add_f32_e32 v163, 1.0, v163
	v_sqrt_f32_e32 v162, v162
	v_rcp_f32_e32 v163, v163
	v_mul_f32_e32 v145, v145, v229
	v_exp_f32_e32 v102, v102
	v_mul_f32_e32 v145, v162, v145
	v_mul_f32_e32 v162, 0xbfb8aa3b, v201
	v_mul_f32_e32 v163, v120, v163
	v_exp_f32_e32 v162, v162
	v_exp_f32_e32 v163, v163
	ds_write2_b32 v181, v164, v145 offset0:128 offset1:144
	v_exp_f32_e32 v98, v98
	v_add_f32_e32 v145, 1.0, v162
	ds_write2_b32 v182, v169, v163 offset0:192 offset1:208
	v_fma_f32 v162, -v163, v163, 1.0 clamp
	v_mul_f32_e32 v163, 0xbfb8aa3b, v186
	v_rcp_f32_e32 v145, v145
	v_exp_f32_e32 v163, v163
	v_sqrt_f32_e32 v162, v162
	v_mul_f32_e32 v145, v145, v231
	v_add_f32_e32 v163, 1.0, v163
	v_rcp_f32_e32 v163, v163
	v_mul_f32_e32 v145, v162, v145
	v_mul_f32_e32 v162, 0xbfb8aa3b, v202
	v_exp_f32_e32 v162, v162
	v_mul_f32_e32 v163, v123, v163
	v_exp_f32_e32 v178, v163
	ds_write2_b32 v181, v166, v145 offset0:192 offset1:208
	v_add_f32_e32 v145, 1.0, v162
	v_mul_f32_e32 v162, 0xbfb8aa3b, v187
	v_mul_f32_e32 v99, 0xbfb8aa3b, v99
	v_exp_f32_e32 v165, v162
	v_exp_f32_e32 v99, v99
	v_add_f32_e32 v102, 1.0, v102
	ds_write2_b32 v182, v178, v98 offset0:32 offset1:48
	v_fma_f32 v98, -v98, v98, 1.0 clamp
	v_add_f32_e32 v165, 1.0, v165
	v_rcp_f32_e32 v102, v102
	v_add_f32_e32 v99, 1.0, v99
	v_rcp_f32_e32 v165, v165
	v_sqrt_f32_e32 v98, v98
	v_rcp_f32_e32 v99, v99
	v_fma_f32 v164, -v178, v178, 1.0 clamp
	v_rcp_f32_e32 v145, v145
	v_mul_f32_e32 v102, v102, v233
	v_sqrt_f32_e32 v164, v164
	v_mul_f32_e32 v165, v123, v165
	v_mul_f32_e32 v98, v98, v102
	v_mul_f32_e32 v102, 0xbfb8aa3b, v103
	v_mul_f32_e32 v99, v122, v99
	v_exp_f32_e32 v179, v165
	v_exp_f32_e32 v102, v102
	v_exp_f32_e32 v99, v99
	v_mul_f32_e32 v145, v145, v232
	v_mul_f32_e32 v162, 0xbfb8aa3b, v203
	v_mul_f32_e32 v145, v164, v145
	v_mul_f32_e32 v164, 0xbfb8aa3b, v188
	v_exp_f32_e32 v162, v162
	v_exp_f32_e32 v167, v164
	ds_write2_b32 v181, v145, v98 offset0:32 offset1:48
	v_add_f32_e32 v98, 1.0, v102
	ds_write2_b32 v182, v179, v99 offset0:96 offset1:112
	v_fma_f32 v99, -v99, v99, 1.0 clamp
	v_rcp_f32_e32 v98, v98
	v_sqrt_f32_e32 v99, v99
	v_add_f32_e32 v162, 1.0, v162
	v_fma_f32 v166, -v179, v179, 1.0 clamp
	v_rcp_f32_e32 v162, v162
	v_mul_f32_e32 v100, 0xbfb8aa3b, v100
	v_mul_f32_e32 v98, v98, v235
	v_sqrt_f32_e32 v166, v166
	v_exp_f32_e32 v100, v100
	v_mul_f32_e32 v98, v99, v98
	v_mul_f32_e32 v99, 0xbfb8aa3b, v104
	v_exp_f32_e32 v99, v99
	v_mul_f32_e32 v162, v162, v234
	v_add_f32_e32 v167, 1.0, v167
	v_mul_f32_e32 v162, v166, v162
	v_add_f32_e32 v100, 1.0, v100
	v_rcp_f32_e32 v167, v167
	v_mul_f32_e32 v164, 0xbfb8aa3b, v204
	v_mul_f32_e32 v166, 0xbfb8aa3b, v189
	v_rcp_f32_e32 v100, v100
	ds_write2_b32 v181, v162, v98 offset0:96 offset1:112
	v_add_f32_e32 v98, 1.0, v99
	v_mul_f32_e32 v99, 0xbfb8aa3b, v101
	v_exp_f32_e32 v164, v164
	v_exp_f32_e32 v169, v166
	v_exp_f32_e32 v99, v99
	v_mul_f32_e32 v167, v123, v167
	v_mul_f32_e32 v100, v122, v100
	v_exp_f32_e32 v180, v167
	v_add_f32_e32 v164, 1.0, v164
	v_add_f32_e32 v169, 1.0, v169
	v_exp_f32_e32 v100, v100
	v_add_f32_e32 v99, 1.0, v99
	v_rcp_f32_e32 v164, v164
	v_rcp_f32_e32 v169, v169
	v_rcp_f32_e32 v99, v99
	v_fma_f32 v168, -v180, v180, 1.0 clamp
	ds_write2_b32 v182, v180, v100 offset0:160 offset1:176
	v_fma_f32 v100, -v100, v100, 1.0 clamp
	v_mul_f32_e32 v164, v164, v236
	v_mul_f32_e32 v166, 0xbfb8aa3b, v205
	v_mul_f32_e32 v169, v123, v169
	v_rcp_f32_e32 v98, v98
	v_mul_f32_e32 v101, 0xbfb8aa3b, v105
	v_mul_f32_e32 v99, v122, v99
	v_sqrt_f32_e32 v168, v168
	v_exp_f32_e32 v166, v166
	v_exp_f32_e32 v183, v169
	v_sqrt_f32_e32 v100, v100
	v_exp_f32_e32 v101, v101
	v_exp_f32_e32 v99, v99
	v_mul_f32_e32 v98, v98, v237
	v_mul_f32_e32 v164, v168, v164
	v_add_f32_e32 v166, 1.0, v166
	v_fma_f32 v185, -v183, v183, 1.0 clamp
	v_mul_f32_e32 v98, v100, v98
	v_add_f32_e32 v100, 1.0, v101
	v_fma_f32 v101, -v99, v99, 1.0 clamp
	v_rcp_f32_e32 v166, v166
	v_rcp_f32_e32 v100, v100
	v_sqrt_f32_e32 v185, v185
	v_sqrt_f32_e32 v101, v101
	v_mul_f32_e32 v166, v166, v238
	ds_write2_b32 v181, v164, v98 offset0:160 offset1:176
	ds_write2_b32 v182, v183, v99 offset0:224 offset1:240
	v_mul_f32_e32 v98, v100, v239
	v_mul_f32_e32 v166, v185, v166
	v_mul_f32_e32 v98, v101, v98
	ds_write2_b32 v181, v166, v98 offset0:224 offset1:240
	s_waitcnt lgkmcnt(0)
	ds_read2st64_b32 v[98:99], v1 offset0:32 offset1:33
	ds_read2st64_b32 v[100:101], v1 offset0:16 offset1:17
	ds_read2st64_b32 v[102:103], v1 offset0:18 offset1:19
	ds_read2st64_b32 v[104:105], v1 offset0:20 offset1:21
	ds_read2st64_b32 v[162:163], v1 offset0:22 offset1:23
	ds_read2st64_b32 v[164:165], v1 offset0:34 offset1:35
	ds_read2st64_b32 v[166:167], v1 offset0:36 offset1:37
	ds_read2st64_b32 v[168:169], v1 offset0:38 offset1:39
	ds_read2st64_b32 v[206:207], v1 offset0:40 offset1:41
	ds_read2st64_b32 v[208:209], v1 offset0:24 offset1:25
	ds_read2st64_b32 v[210:211], v1 offset0:26 offset1:27
	ds_read2st64_b32 v[212:213], v1 offset0:28 offset1:29
	ds_read2st64_b32 v[214:215], v1 offset0:30 offset1:31
	ds_read2st64_b32 v[216:217], v1 offset0:42 offset1:43
	ds_read2st64_b32 v[218:219], v1 offset0:44 offset1:45
	ds_read2st64_b32 v[220:221], v1 offset0:46 offset1:47
	s_waitcnt lgkmcnt(14)
	v_fma_f32 v98, 0, v100, v98
	v_fmac_f32_e32 v99, v98, v101
	v_mul_f32_e32 v101, v100, v101
	s_waitcnt lgkmcnt(10)
	v_fma_f32 v98, v99, v102, v164
	v_fmac_f32_e32 v165, v98, v103
	v_mul_f32_e32 v101, v101, v102
	v_mul_f32_e32 v101, v101, v103
	s_waitcnt lgkmcnt(9)
	v_fma_f32 v98, v165, v104, v166
	v_fmac_f32_e32 v167, v98, v105
	v_mul_f32_e32 v101, v101, v104
	v_mul_f32_e32 v101, v101, v105
	s_waitcnt lgkmcnt(8)
	v_fma_f32 v98, v167, v162, v168
	v_fmac_f32_e32 v169, v98, v163
	v_mul_f32_e32 v101, v101, v162
	v_mul_f32_e32 v101, v101, v163
	s_waitcnt lgkmcnt(6)
	v_fmac_f32_e32 v206, v169, v208
	v_mul_f32_e32 v101, v101, v208
	v_fmac_f32_e32 v207, v206, v209
	v_mul_f32_e32 v101, v101, v209
	s_waitcnt lgkmcnt(2)
	v_fmac_f32_e32 v216, v207, v210
	v_mul_f32_e32 v101, v101, v210
	v_fmac_f32_e32 v217, v216, v211
	v_mul_f32_e32 v101, v101, v211
	s_waitcnt lgkmcnt(1)
	v_fmac_f32_e32 v218, v217, v212
	v_mul_f32_e32 v101, v101, v212
	v_fmac_f32_e32 v219, v218, v213
	v_mul_f32_e32 v101, v101, v213
	s_waitcnt lgkmcnt(0)
	v_fmac_f32_e32 v220, v219, v214
	v_mul_f32_e32 v101, v101, v214
	v_fmac_f32_e32 v221, v220, v215
	v_mul_f32_e32 v101, v101, v215
	v_mov_b32_e32 v98, v221
	s_branch .LBB0_934
